# MLA loop: generic iteration moved out of line, tile loads unconditional with clamped scalar base advance
# baseline (speedup 1.0000x reference)
; #define LAS __attribute__((address_space(3)))
; template <int DQK, int DV, int FLAGS, int qp, int kp, int vts, int op> ...
;     ...
; #pragma unroll
;             for (int c = 0; c < ND0 / 2; ++c) {
;                 if (c + 1 < ND0 / 2) {
; #pragma unroll
;                     for (int i = 0; i < 2; ++i) { kf[(c + 1) & 1][2 * i] = *(const LAS bf16x8*)(kb + (2 * c + 2 + i) * 32); kf[(c + 1) & 1][2 * i + 1] = *(const LAS bf16x8*)(kb + 32 * KROW + (2 * c + 2 + i) * 32); }
;                 }
; #pragma unroll
;                 for (int i = 0; i < 2; ++i) {
;                     p0 = __builtin_amdgcn_mfma_f32_32x32x16_bf16(kf[c & 1][2 * i], qr[2 * c + i], p0, 0, 0, 0);
;                     p1 = __builtin_amdgcn_mfma_f32_32x32x16_bf16(kf[c & 1][2 * i + 1], qr[2 * c + i], p1, 0, 0, 0);
;                 }
;                 __builtin_amdgcn_sched_barrier(0);
;             }
;             if (more) ATT_GLOAD((FLAGS & AF_REV) ? t - 1 : t + 1);
;             bf16x8 vf[2][4];
; #pragma unroll
;             for (int ks = 0; ks < 4; ++ks) vf[0][ks] = *(const LAS bf16x8*)(vb + ks * 32);
;     ...
;             f32x2 rs2 = {0.f, 0.f};
; #pragma unroll
;             for (int r = 0; r < 16; ++r) { p0[r] = __builtin_amdgcn_exp2f(p0[r]); p1[r] = __builtin_amdgcn_exp2f(p1[r]); }
; #pragma unroll
;             for (int r = 0; r < 16; r += 2) { rs2 += (f32x2){p0[r], p0[r + 1]}; rs2 += (f32x2){p1[r], p1[r + 1]}; }
;             l += rs2.x + rs2.y;
;             bf16x8 pf[4];
;             pf[0] = pack_bf16x8(p0, 0); pf[1] = pack_bf16x8(p0, 8); pf[2] = pack_bf16x8(p1, 0); pf[3] = pack_bf16x8(p1, 8);
;             __builtin_amdgcn_sched_barrier(0);
; #pragma unroll
;             for (int d = 0; d < NDB; ++d) {
;                 if (d + 1 < NDB) {
; #pragma unroll
;                     for (int ks = 0; ks < 4; ++ks) vf[(d + 1) & 1][ks] = *(const LAS bf16x8*)(vb + (d + 1) * 32 * VROW + ks * 32);
;                 }
; #pragma unroll
;                 for (int ks = 0; ks < 4; ++ks) o[d] = __builtin_amdgcn_mfma_f32_32x32x16_bf16(vf[d & 1][ks], pf[ks], o[d], 0, 0, 0);
;                 __builtin_amdgcn_sched_barrier(0);
;             }
.Lq_top0:
	s_cmp_eq_u32 s3, 0
	s_cbranch_scc1 .Lq_gen0
	s_add_i32 s13, s3, 1
	s_cmp_ge_i32 s13, s20
	s_cbranch_scc1 .Lq_gen0
	ds_read_b128 v[96:99], v187 offset:22528
	ds_read_b128 v[104:107], v187 offset:29184
	ds_read_b128 v[100:103], v187 offset:22560
	ds_read_b128 v[108:111], v187 offset:29216
	ds_read_b128 v[112:115], v187 offset:22592
	ds_read_b128 v[120:123], v187 offset:29248
	ds_read_b128 v[116:119], v187 offset:22624
	ds_read_b128 v[124:127], v187 offset:29280
	v_mfma_f32_32x32x16_bf16 v[32:47], v[152:155], v[214:217], v[32:47]
	v_exp_f32_e32 v64, v64
	v_exp_f32_e32 v65, v65
	v_mfma_f32_32x32x16_bf16 v[16:31], v[188:191], v[214:217], v[16:31]
	v_exp_f32_e32 v80, v80
	v_exp_f32_e32 v81, v81
	v_add_f32_e32 v204, v64, v175
	s_waitcnt vmcnt(0)
	ds_write_b128 v248, v[140:143] offset:0
	v_mfma_f32_32x32x16_bf16 v[32:47], v[156:159], v[218:221], v[32:47]
	v_exp_f32_e32 v66, v66
	v_exp_f32_e32 v67, v67
	v_add_f32_e32 v204, v80, v204
	v_add_f32_e32 v205, v65, v81
	ds_write_b128 v249, v[148:151] offset:13312
	v_mfma_f32_32x32x16_bf16 v[16:31], v[192:195], v[218:221], v[16:31]
	v_exp_f32_e32 v82, v82
	v_exp_f32_e32 v83, v83
	v_add_f32_e32 v204, v66, v204
	v_add_f32_e32 v205, v67, v205
	s_and_saveexec_b64 s[14:15], s[10:11]
	ds_write_b128 v250, v[144:147] offset:0
	s_or_b64 exec, exec, s[14:15]
	v_mfma_f32_32x32x16_bf16 v[32:47], v[160:163], v[222:225], v[32:47]
	v_exp_f32_e32 v68, v68
	v_exp_f32_e32 v69, v69
	v_add_f32_e32 v204, v82, v204
	v_add_f32_e32 v205, v83, v205
	s_and_saveexec_b64 s[14:15], s[10:11]
	global_load_dwordx4 v[144:147], v180, s[98:99]
	s_or_b64 exec, exec, s[14:15]
	v_mfma_f32_32x32x16_bf16 v[16:31], v[196:199], v[222:225], v[16:31]
	v_exp_f32_e32 v84, v84
	v_exp_f32_e32 v85, v85
	v_add_f32_e32 v204, v68, v204
	v_add_f32_e32 v205, v69, v205
	global_load_dwordx4 v[140:143], v178, s[98:99]
	v_mfma_f32_32x32x16_bf16 v[32:47], v[164:167], v[226:229], v[32:47]
	v_exp_f32_e32 v70, v70
	v_exp_f32_e32 v71, v71
	v_add_f32_e32 v204, v84, v204
	v_add_f32_e32 v205, v85, v205
	global_load_dwordx4 v[148:151], v176, s[100:101]
	s_add_i32 s12, s3, 4
	s_cmp_lt_i32 s12, s2
	s_cselect_b32 s12, s96, 0
	s_cselect_b32 s13, 0x80, 0
	s_add_u32 s98, s98, s12
	s_addc_u32 s99, s99, 0
	s_add_u32 s100, s100, s13
	s_addc_u32 s101, s101, 0
	v_mfma_f32_32x32x16_bf16 v[16:31], v[200:203], v[226:229], v[16:31]
	v_exp_f32_e32 v86, v86
	v_exp_f32_e32 v87, v87
	v_add_f32_e32 v204, v70, v204
	v_add_f32_e32 v205, v71, v205
	ds_read_b128 v[152:155], v246 offset:13312
	ds_read_b128 v[156:159], v246 offset:13344
	ds_read_b128 v[160:163], v246 offset:13376
	ds_read_b128 v[164:167], v246 offset:13408
	s_waitcnt lgkmcnt(8)
	v_mfma_f32_32x32x16_bf16 v[214:229], v[96:99], v[2:5], v[48:63]
	v_exp_f32_e32 v72, v72
	v_exp_f32_e32 v73, v73
	v_add_f32_e32 v204, v86, v204
	v_add_f32_e32 v205, v87, v205
	v_mfma_f32_32x32x16_bf16 v[230:245], v[104:107], v[2:5], v[48:63]
	v_exp_f32_e32 v88, v88
	v_exp_f32_e32 v89, v89
	v_add_f32_e32 v204, v72, v204
	v_add_f32_e32 v205, v73, v205
	v_mfma_f32_32x32x16_bf16 v[214:229], v[100:103], v[6:9], v[214:229]
	v_exp_f32_e32 v74, v74
	v_exp_f32_e32 v75, v75
	v_add_f32_e32 v204, v88, v204
	v_add_f32_e32 v205, v89, v205
	v_mfma_f32_32x32x16_bf16 v[230:245], v[108:111], v[6:9], v[230:245]
	v_exp_f32_e32 v90, v90
	v_exp_f32_e32 v91, v91
	v_add_f32_e32 v204, v74, v204
	v_add_f32_e32 v205, v75, v205
	ds_read_b128 v[96:99], v187 offset:22656
	ds_read_b128 v[104:107], v187 offset:29312
	ds_read_b128 v[100:103], v187 offset:22688
	ds_read_b128 v[108:111], v187 offset:29344
	s_waitcnt lgkmcnt(8)
	v_mfma_f32_32x32x16_bf16 v[214:229], v[112:115], v[10:13], v[214:229]
	v_exp_f32_e32 v76, v76
	v_exp_f32_e32 v77, v77
	v_add_f32_e32 v204, v90, v204
	v_add_f32_e32 v205, v91, v205
	v_mfma_f32_32x32x16_bf16 v[230:245], v[120:123], v[10:13], v[230:245]
	v_exp_f32_e32 v92, v92
	v_exp_f32_e32 v93, v93
	v_add_f32_e32 v204, v76, v204
	v_add_f32_e32 v205, v77, v205
	v_mfma_f32_32x32x16_bf16 v[214:229], v[116:119], v[128:131], v[214:229]
	v_exp_f32_e32 v78, v78
	v_exp_f32_e32 v79, v79
	v_add_f32_e32 v204, v92, v204
	v_add_f32_e32 v205, v93, v205
	v_mfma_f32_32x32x16_bf16 v[230:245], v[124:127], v[128:131], v[230:245]
	v_exp_f32_e32 v94, v94
	v_exp_f32_e32 v95, v95
	v_add_f32_e32 v204, v78, v204
	v_add_f32_e32 v205, v79, v205
	ds_read_b128 v[188:191], v246 offset:17920
	ds_read_b128 v[192:195], v246 offset:17952
	ds_read_b128 v[196:199], v246 offset:17984
	ds_read_b128 v[200:203], v246 offset:18016
	s_waitcnt lgkmcnt(4)
	v_mfma_f32_32x32x16_bf16 v[214:229], v[96:99], v[132:135], v[214:229]
	s_nop 0
	v_add_f32_e32 v204, v94, v204
	v_add_f32_e32 v205, v95, v205
	v_cvt_pk_bf16_f32 v64, v64, v65
	v_cvt_pk_bf16_f32 v65, v66, v67
	v_cvt_pk_bf16_f32 v66, v68, v69
	v_mfma_f32_32x32x16_bf16 v[230:245], v[104:107], v[132:135], v[230:245]
	v_cvt_pk_bf16_f32 v67, v70, v71
	v_cvt_pk_bf16_f32 v68, v72, v73
	v_cvt_pk_bf16_f32 v69, v74, v75
	v_cvt_pk_bf16_f32 v70, v76, v77
	v_cvt_pk_bf16_f32 v71, v78, v79
	v_mfma_f32_32x32x16_bf16 v[214:229], v[100:103], v[136:139], v[214:229]
	v_cvt_pk_bf16_f32 v72, v80, v81
	v_cvt_pk_bf16_f32 v73, v82, v83
	v_cvt_pk_bf16_f32 v74, v84, v85
	v_cvt_pk_bf16_f32 v75, v86, v87
	v_cvt_pk_bf16_f32 v76, v88, v89
	v_mfma_f32_32x32x16_bf16 v[230:245], v[108:111], v[136:139], v[230:245]
	v_cvt_pk_bf16_f32 v77, v90, v91
	v_cvt_pk_bf16_f32 v78, v92, v93
	v_cvt_pk_bf16_f32 v79, v94, v95
	v_add_f32_e32 v175, v204, v205

; #define LAS __attribute__((address_space(3)))
; template <int DQK, int DV, int FLAGS, int qp, int kp, int vts, int op> ...
;     ...
; #pragma unroll
;             for (int c = 0; c < ND0 / 2; ++c) {
;                 if (c + 1 < ND0 / 2) {
; #pragma unroll
;                     for (int i = 0; i < 2; ++i) { kf[(c + 1) & 1][2 * i] = *(const LAS bf16x8*)(kb + (2 * c + 2 + i) * 32); kf[(c + 1) & 1][2 * i + 1] = *(const LAS bf16x8*)(kb + 32 * KROW + (2 * c + 2 + i) * 32); }
;                 }
; #pragma unroll
;                 for (int i = 0; i < 2; ++i) {
;                     p0 = __builtin_amdgcn_mfma_f32_32x32x16_bf16(kf[c & 1][2 * i], qr[2 * c + i], p0, 0, 0, 0);
;                     p1 = __builtin_amdgcn_mfma_f32_32x32x16_bf16(kf[c & 1][2 * i + 1], qr[2 * c + i], p1, 0, 0, 0);
;                 }
;                 __builtin_amdgcn_sched_barrier(0);
;             }
;             if (more) ATT_GLOAD((FLAGS & AF_REV) ? t - 1 : t + 1);
;             bf16x8 vf[2][4];
; #pragma unroll
;             for (int ks = 0; ks < 4; ++ks) vf[0][ks] = *(const LAS bf16x8*)(vb + ks * 32);
;     ...
;             f32x2 rs2 = {0.f, 0.f};
; #pragma unroll
;             for (int r = 0; r < 16; ++r) { p0[r] = __builtin_amdgcn_exp2f(p0[r]); p1[r] = __builtin_amdgcn_exp2f(p1[r]); }
; #pragma unroll
;             for (int r = 0; r < 16; r += 2) { rs2 += (f32x2){p0[r], p0[r + 1]}; rs2 += (f32x2){p1[r], p1[r + 1]}; }
;             l += rs2.x + rs2.y;
;             bf16x8 pf[4];
;             pf[0] = pack_bf16x8(p0, 0); pf[1] = pack_bf16x8(p0, 8); pf[2] = pack_bf16x8(p1, 0); pf[3] = pack_bf16x8(p1, 8);
;             __builtin_amdgcn_sched_barrier(0);
; #pragma unroll
;             for (int d = 0; d < NDB; ++d) {
;                 if (d + 1 < NDB) {
; #pragma unroll
;                     for (int ks = 0; ks < 4; ++ks) vf[(d + 1) & 1][ks] = *(const LAS bf16x8*)(vb + (d + 1) * 32 * VROW + ks * 32);
;                 }
; #pragma unroll
;                 for (int ks = 0; ks < 4; ++ks) o[d] = __builtin_amdgcn_mfma_f32_32x32x16_bf16(vf[d & 1][ks], pf[ks], o[d], 0, 0, 0);
;                 __builtin_amdgcn_sched_barrier(0);
;             }
.Lq_top1:
	s_cmp_eq_u32 s3, 0
	s_cbranch_scc1 .Lq_gen1
	s_add_i32 s13, s3, 1
	s_cmp_ge_i32 s13, s20
	s_cbranch_scc1 .Lq_gen1
	ds_read_b128 v[96:99], v213 offset:0
	ds_read_b128 v[104:107], v213 offset:6656
	ds_read_b128 v[100:103], v213 offset:32
	ds_read_b128 v[108:111], v213 offset:6688
	ds_read_b128 v[112:115], v213 offset:64
	ds_read_b128 v[120:123], v213 offset:6720
	ds_read_b128 v[116:119], v213 offset:96
	ds_read_b128 v[124:127], v213 offset:6752
	v_mfma_f32_32x32x16_bf16 v[32:47], v[152:155], v[64:67], v[32:47]
	v_exp_f32_e32 v214, v214
	v_exp_f32_e32 v215, v215
	v_mfma_f32_32x32x16_bf16 v[16:31], v[188:191], v[64:67], v[16:31]
	v_exp_f32_e32 v230, v230
	v_exp_f32_e32 v231, v231
	v_add_f32_e32 v204, v214, v175
	s_waitcnt vmcnt(0)
	ds_write_b128 v248, v[140:143] offset:22528
	v_mfma_f32_32x32x16_bf16 v[32:47], v[156:159], v[68:71], v[32:47]
	v_exp_f32_e32 v216, v216
	v_exp_f32_e32 v217, v217
	v_add_f32_e32 v204, v230, v204
	v_add_f32_e32 v205, v215, v231
	ds_write_b128 v249, v[148:151] offset:35840
	v_mfma_f32_32x32x16_bf16 v[16:31], v[192:195], v[68:71], v[16:31]
	v_exp_f32_e32 v232, v232
	v_exp_f32_e32 v233, v233
	v_add_f32_e32 v204, v216, v204
	v_add_f32_e32 v205, v217, v205
	s_and_saveexec_b64 s[14:15], s[10:11]
	ds_write_b128 v250, v[144:147] offset:22528
	s_or_b64 exec, exec, s[14:15]
	v_mfma_f32_32x32x16_bf16 v[32:47], v[160:163], v[72:75], v[32:47]
	v_exp_f32_e32 v218, v218
	v_exp_f32_e32 v219, v219
	v_add_f32_e32 v204, v232, v204
	v_add_f32_e32 v205, v233, v205
	s_and_saveexec_b64 s[14:15], s[10:11]
	global_load_dwordx4 v[144:147], v180, s[98:99]
	s_or_b64 exec, exec, s[14:15]
	v_mfma_f32_32x32x16_bf16 v[16:31], v[196:199], v[72:75], v[16:31]
	v_exp_f32_e32 v234, v234
	v_exp_f32_e32 v235, v235
	v_add_f32_e32 v204, v218, v204
	v_add_f32_e32 v205, v219, v205
	global_load_dwordx4 v[140:143], v178, s[98:99]
	v_mfma_f32_32x32x16_bf16 v[32:47], v[164:167], v[76:79], v[32:47]
	v_exp_f32_e32 v220, v220
	v_exp_f32_e32 v221, v221
	v_add_f32_e32 v204, v234, v204
	v_add_f32_e32 v205, v235, v205
	global_load_dwordx4 v[148:151], v176, s[100:101]
	s_add_i32 s12, s3, 4
	s_cmp_lt_i32 s12, s2
	s_cselect_b32 s12, s96, 0
	s_cselect_b32 s13, 0x80, 0
	s_add_u32 s98, s98, s12
	s_addc_u32 s99, s99, 0
	s_add_u32 s100, s100, s13
	s_addc_u32 s101, s101, 0
	v_mfma_f32_32x32x16_bf16 v[16:31], v[200:203], v[76:79], v[16:31]
	v_exp_f32_e32 v236, v236
	v_exp_f32_e32 v237, v237
	v_add_f32_e32 v204, v220, v204
	v_add_f32_e32 v205, v221, v205
	ds_read_b128 v[152:155], v246 offset:35840
	ds_read_b128 v[156:159], v246 offset:35872
	ds_read_b128 v[160:163], v246 offset:35904
	ds_read_b128 v[164:167], v246 offset:35936
	s_waitcnt lgkmcnt(8)
	v_mfma_f32_32x32x16_bf16 v[64:79], v[96:99], v[2:5], v[48:63]
	v_exp_f32_e32 v222, v222
	v_exp_f32_e32 v223, v223
	v_add_f32_e32 v204, v236, v204
	v_add_f32_e32 v205, v237, v205
	v_mfma_f32_32x32x16_bf16 v[80:95], v[104:107], v[2:5], v[48:63]
	v_exp_f32_e32 v238, v238
	v_exp_f32_e32 v239, v239
	v_add_f32_e32 v204, v222, v204
	v_add_f32_e32 v205, v223, v205
	v_mfma_f32_32x32x16_bf16 v[64:79], v[100:103], v[6:9], v[64:79]
	v_exp_f32_e32 v224, v224
	v_exp_f32_e32 v225, v225
	v_add_f32_e32 v204, v238, v204
	v_add_f32_e32 v205, v239, v205
	v_mfma_f32_32x32x16_bf16 v[80:95], v[108:111], v[6:9], v[80:95]
	v_exp_f32_e32 v240, v240
	v_exp_f32_e32 v241, v241
	v_add_f32_e32 v204, v224, v204
	v_add_f32_e32 v205, v225, v205
	ds_read_b128 v[96:99], v213 offset:128
	ds_read_b128 v[104:107], v213 offset:6784
	ds_read_b128 v[100:103], v213 offset:160
	ds_read_b128 v[108:111], v213 offset:6816
	s_waitcnt lgkmcnt(8)
	v_mfma_f32_32x32x16_bf16 v[64:79], v[112:115], v[10:13], v[64:79]
	v_exp_f32_e32 v226, v226
	v_exp_f32_e32 v227, v227
	v_add_f32_e32 v204, v240, v204
	v_add_f32_e32 v205, v241, v205
	v_mfma_f32_32x32x16_bf16 v[80:95], v[120:123], v[10:13], v[80:95]
	v_exp_f32_e32 v242, v242
	v_exp_f32_e32 v243, v243
	v_add_f32_e32 v204, v226, v204
	v_add_f32_e32 v205, v227, v205
	v_mfma_f32_32x32x16_bf16 v[64:79], v[116:119], v[128:131], v[64:79]
	v_exp_f32_e32 v228, v228
	v_exp_f32_e32 v229, v229
	v_add_f32_e32 v204, v242, v204
	v_add_f32_e32 v205, v243, v205
	v_mfma_f32_32x32x16_bf16 v[80:95], v[124:127], v[128:131], v[80:95]
	v_exp_f32_e32 v244, v244
	v_exp_f32_e32 v245, v245
	v_add_f32_e32 v204, v228, v204
	v_add_f32_e32 v205, v229, v205
	ds_read_b128 v[188:191], v246 offset:40448
	ds_read_b128 v[192:195], v246 offset:40480
	ds_read_b128 v[196:199], v246 offset:40512
	ds_read_b128 v[200:203], v246 offset:40544
	s_waitcnt lgkmcnt(4)
	v_mfma_f32_32x32x16_bf16 v[64:79], v[96:99], v[132:135], v[64:79]
	s_nop 0
	v_add_f32_e32 v204, v244, v204
	v_add_f32_e32 v205, v245, v205
	v_cvt_pk_bf16_f32 v214, v214, v215
	v_cvt_pk_bf16_f32 v215, v216, v217
	v_cvt_pk_bf16_f32 v216, v218, v219
	v_mfma_f32_32x32x16_bf16 v[80:95], v[104:107], v[132:135], v[80:95]
	v_cvt_pk_bf16_f32 v217, v220, v221
	v_cvt_pk_bf16_f32 v218, v222, v223
	v_cvt_pk_bf16_f32 v219, v224, v225
	v_cvt_pk_bf16_f32 v220, v226, v227
	v_cvt_pk_bf16_f32 v221, v228, v229
	v_mfma_f32_32x32x16_bf16 v[64:79], v[100:103], v[136:139], v[64:79]
	v_cvt_pk_bf16_f32 v222, v230, v231
	v_cvt_pk_bf16_f32 v223, v232, v233
	v_cvt_pk_bf16_f32 v224, v234, v235
	v_cvt_pk_bf16_f32 v225, v236, v237
	v_cvt_pk_bf16_f32 v226, v238, v239
	v_mfma_f32_32x32x16_bf16 v[80:95], v[108:111], v[136:139], v[80:95]
	v_cvt_pk_bf16_f32 v227, v240, v241
	v_cvt_pk_bf16_f32 v228, v242, v243
	v_cvt_pk_bf16_f32 v229, v244, v245
	v_add_f32_e32 v175, v204, v205

; #define LAS __attribute__((address_space(3)))
; template <int DQK, int DV, int FLAGS, int qp, int kp, int vts, int op> ...
;     ...
; #pragma unroll
;             for (int c = 0; c < ND0 / 2; ++c) {
;                 if (c + 1 < ND0 / 2) {
; #pragma unroll
;                     for (int i = 0; i < 2; ++i) { kf[(c + 1) & 1][2 * i] = *(const LAS bf16x8*)(kb + (2 * c + 2 + i) * 32); kf[(c + 1) & 1][2 * i + 1] = *(const LAS bf16x8*)(kb + 32 * KROW + (2 * c + 2 + i) * 32); }
;                 }
; #pragma unroll
;                 for (int i = 0; i < 2; ++i) {
;                     p0 = __builtin_amdgcn_mfma_f32_32x32x16_bf16(kf[c & 1][2 * i], qr[2 * c + i], p0, 0, 0, 0);
;                     p1 = __builtin_amdgcn_mfma_f32_32x32x16_bf16(kf[c & 1][2 * i + 1], qr[2 * c + i], p1, 0, 0, 0);
;                 }
;                 __builtin_amdgcn_sched_barrier(0);
;             }
;             if (more) ATT_GLOAD((FLAGS & AF_REV) ? t - 1 : t + 1);
;             bf16x8 vf[2][4];
; #pragma unroll
;             for (int ks = 0; ks < 4; ++ks) vf[0][ks] = *(const LAS bf16x8*)(vb + ks * 32);
;     ...
;             f32x2 rs2 = {0.f, 0.f};
; #pragma unroll
;             for (int r = 0; r < 16; ++r) { p0[r] = __builtin_amdgcn_exp2f(p0[r]); p1[r] = __builtin_amdgcn_exp2f(p1[r]); }
; #pragma unroll
;             for (int r = 0; r < 16; r += 2) { rs2 += (f32x2){p0[r], p0[r + 1]}; rs2 += (f32x2){p1[r], p1[r + 1]}; }
;             l += rs2.x + rs2.y;
;             bf16x8 pf[4];
;             pf[0] = pack_bf16x8(p0, 0); pf[1] = pack_bf16x8(p0, 8); pf[2] = pack_bf16x8(p1, 0); pf[3] = pack_bf16x8(p1, 8);
;             __builtin_amdgcn_sched_barrier(0);
; #pragma unroll
;             for (int d = 0; d < NDB; ++d) {
;                 if (d + 1 < NDB) {
; #pragma unroll
;                     for (int ks = 0; ks < 4; ++ks) vf[(d + 1) & 1][ks] = *(const LAS bf16x8*)(vb + (d + 1) * 32 * VROW + ks * 32);
;                 }
; #pragma unroll
;                 for (int ks = 0; ks < 4; ++ks) o[d] = __builtin_amdgcn_mfma_f32_32x32x16_bf16(vf[d & 1][ks], pf[ks], o[d], 0, 0, 0);
;                 __builtin_amdgcn_sched_barrier(0);
;             }
.Lq_top2:
	s_cmp_eq_u32 s3, 0
	s_cbranch_scc1 .Lq_gen2
	s_add_i32 s13, s3, 1
	s_cmp_ge_i32 s13, s20
	s_cbranch_scc1 .Lq_gen2
	ds_read_b128 v[96:99], v213 offset:22528
	ds_read_b128 v[104:107], v213 offset:29184
	ds_read_b128 v[100:103], v213 offset:22560
	ds_read_b128 v[108:111], v213 offset:29216
	ds_read_b128 v[112:115], v213 offset:22592
	ds_read_b128 v[120:123], v213 offset:29248
	ds_read_b128 v[116:119], v213 offset:22624
	ds_read_b128 v[124:127], v213 offset:29280
	v_mfma_f32_32x32x16_bf16 v[32:47], v[152:155], v[214:217], v[32:47]
	v_exp_f32_e32 v64, v64
	v_exp_f32_e32 v65, v65
	v_mfma_f32_32x32x16_bf16 v[16:31], v[188:191], v[214:217], v[16:31]
	v_exp_f32_e32 v80, v80
	v_exp_f32_e32 v81, v81
	v_add_f32_e32 v204, v64, v175
	s_waitcnt vmcnt(0)
	ds_write_b128 v14, v[140:143] offset:0
	v_mfma_f32_32x32x16_bf16 v[32:47], v[156:159], v[218:221], v[32:47]
	v_exp_f32_e32 v66, v66
	v_exp_f32_e32 v67, v67
	v_add_f32_e32 v204, v80, v204
	v_add_f32_e32 v205, v65, v81
	ds_write_b128 v174, v[148:151] offset:13312
	v_mfma_f32_32x32x16_bf16 v[16:31], v[192:195], v[218:221], v[16:31]
	v_exp_f32_e32 v82, v82
	v_exp_f32_e32 v83, v83
	v_add_f32_e32 v204, v66, v204
	v_add_f32_e32 v205, v67, v205
	s_and_saveexec_b64 s[14:15], s[10:11]
	ds_write_b128 v172, v[144:147] offset:0
	s_or_b64 exec, exec, s[14:15]
	v_mfma_f32_32x32x16_bf16 v[32:47], v[160:163], v[222:225], v[32:47]
	v_exp_f32_e32 v68, v68
	v_exp_f32_e32 v69, v69
	v_add_f32_e32 v204, v82, v204
	v_add_f32_e32 v205, v83, v205
	s_and_saveexec_b64 s[14:15], s[10:11]
	global_load_dwordx4 v[144:147], v180, s[98:99]
	s_or_b64 exec, exec, s[14:15]
	v_mfma_f32_32x32x16_bf16 v[16:31], v[196:199], v[222:225], v[16:31]
	v_exp_f32_e32 v84, v84
	v_exp_f32_e32 v85, v85
	v_add_f32_e32 v204, v68, v204
	v_add_f32_e32 v205, v69, v205
	global_load_dwordx4 v[140:143], v178, s[98:99]
	v_mfma_f32_32x32x16_bf16 v[32:47], v[164:167], v[226:229], v[32:47]
	v_exp_f32_e32 v70, v70
	v_exp_f32_e32 v71, v71
	v_add_f32_e32 v204, v84, v204
	v_add_f32_e32 v205, v85, v205
	global_load_dwordx4 v[148:151], v176, s[100:101]
	s_add_i32 s12, s3, 4
	s_cmp_lt_i32 s12, s2
	s_cselect_b32 s12, s96, 0
	s_cselect_b32 s13, 0x80, 0
	s_add_u32 s98, s98, s12
	s_addc_u32 s99, s99, 0
	s_add_u32 s100, s100, s13
	s_addc_u32 s101, s101, 0
	v_mfma_f32_32x32x16_bf16 v[16:31], v[200:203], v[226:229], v[16:31]
	v_exp_f32_e32 v86, v86
	v_exp_f32_e32 v87, v87
	v_add_f32_e32 v204, v70, v204
	v_add_f32_e32 v205, v71, v205
	ds_read_b128 v[152:155], v247 offset:13312
	ds_read_b128 v[156:159], v247 offset:13344
	ds_read_b128 v[160:163], v247 offset:13376
	ds_read_b128 v[164:167], v247 offset:13408
	s_waitcnt lgkmcnt(8)
	v_mfma_f32_32x32x16_bf16 v[214:229], v[96:99], v[2:5], v[48:63]
	v_exp_f32_e32 v72, v72
	v_exp_f32_e32 v73, v73
	v_add_f32_e32 v204, v86, v204
	v_add_f32_e32 v205, v87, v205
	v_mfma_f32_32x32x16_bf16 v[230:245], v[104:107], v[2:5], v[48:63]
	v_exp_f32_e32 v88, v88
	v_exp_f32_e32 v89, v89
	v_add_f32_e32 v204, v72, v204
	v_add_f32_e32 v205, v73, v205
	v_mfma_f32_32x32x16_bf16 v[214:229], v[100:103], v[6:9], v[214:229]
	v_exp_f32_e32 v74, v74
	v_exp_f32_e32 v75, v75
	v_add_f32_e32 v204, v88, v204
	v_add_f32_e32 v205, v89, v205
	v_mfma_f32_32x32x16_bf16 v[230:245], v[108:111], v[6:9], v[230:245]
	v_exp_f32_e32 v90, v90
	v_exp_f32_e32 v91, v91
	v_add_f32_e32 v204, v74, v204
	v_add_f32_e32 v205, v75, v205
	ds_read_b128 v[96:99], v213 offset:22656
	ds_read_b128 v[104:107], v213 offset:29312
	ds_read_b128 v[100:103], v213 offset:22688
	ds_read_b128 v[108:111], v213 offset:29344
	s_waitcnt lgkmcnt(8)
	v_mfma_f32_32x32x16_bf16 v[214:229], v[112:115], v[10:13], v[214:229]
	v_exp_f32_e32 v76, v76
	v_exp_f32_e32 v77, v77
	v_add_f32_e32 v204, v90, v204
	v_add_f32_e32 v205, v91, v205
	v_mfma_f32_32x32x16_bf16 v[230:245], v[120:123], v[10:13], v[230:245]
	v_exp_f32_e32 v92, v92
	v_exp_f32_e32 v93, v93
	v_add_f32_e32 v204, v76, v204
	v_add_f32_e32 v205, v77, v205
	v_mfma_f32_32x32x16_bf16 v[214:229], v[116:119], v[128:131], v[214:229]
	v_exp_f32_e32 v78, v78
	v_exp_f32_e32 v79, v79
	v_add_f32_e32 v204, v92, v204
	v_add_f32_e32 v205, v93, v205
	v_mfma_f32_32x32x16_bf16 v[230:245], v[124:127], v[128:131], v[230:245]
	v_exp_f32_e32 v94, v94
	v_exp_f32_e32 v95, v95
	v_add_f32_e32 v204, v78, v204
	v_add_f32_e32 v205, v79, v205
	ds_read_b128 v[188:191], v247 offset:17920
	ds_read_b128 v[192:195], v247 offset:17952
	ds_read_b128 v[196:199], v247 offset:17984
	ds_read_b128 v[200:203], v247 offset:18016
	s_waitcnt lgkmcnt(4)
	v_mfma_f32_32x32x16_bf16 v[214:229], v[96:99], v[132:135], v[214:229]
	s_nop 0
	v_add_f32_e32 v204, v94, v204
	v_add_f32_e32 v205, v95, v205
	v_cvt_pk_bf16_f32 v64, v64, v65
	v_cvt_pk_bf16_f32 v65, v66, v67
	v_cvt_pk_bf16_f32 v66, v68, v69
	v_mfma_f32_32x32x16_bf16 v[230:245], v[104:107], v[132:135], v[230:245]
	v_cvt_pk_bf16_f32 v67, v70, v71
	v_cvt_pk_bf16_f32 v68, v72, v73
	v_cvt_pk_bf16_f32 v69, v74, v75
	v_cvt_pk_bf16_f32 v70, v76, v77
	v_cvt_pk_bf16_f32 v71, v78, v79
	v_mfma_f32_32x32x16_bf16 v[214:229], v[100:103], v[136:139], v[214:229]
	v_cvt_pk_bf16_f32 v72, v80, v81
	v_cvt_pk_bf16_f32 v73, v82, v83
	v_cvt_pk_bf16_f32 v74, v84, v85
	v_cvt_pk_bf16_f32 v75, v86, v87
	v_cvt_pk_bf16_f32 v76, v88, v89
	v_mfma_f32_32x32x16_bf16 v[230:245], v[108:111], v[136:139], v[230:245]
	v_cvt_pk_bf16_f32 v77, v90, v91
	v_cvt_pk_bf16_f32 v78, v92, v93
	v_cvt_pk_bf16_f32 v79, v94, v95
	v_add_f32_e32 v175, v204, v205

; #define LAS __attribute__((address_space(3)))
; template <int DQK, int DV, int FLAGS, int qp, int kp, int vts, int op> ...
;     ...
; #pragma unroll
;             for (int c = 0; c < ND0 / 2; ++c) {
;                 if (c + 1 < ND0 / 2) {
; #pragma unroll
;                     for (int i = 0; i < 2; ++i) { kf[(c + 1) & 1][2 * i] = *(const LAS bf16x8*)(kb + (2 * c + 2 + i) * 32); kf[(c + 1) & 1][2 * i + 1] = *(const LAS bf16x8*)(kb + 32 * KROW + (2 * c + 2 + i) * 32); }
;                 }
; #pragma unroll
;                 for (int i = 0; i < 2; ++i) {
;                     p0 = __builtin_amdgcn_mfma_f32_32x32x16_bf16(kf[c & 1][2 * i], qr[2 * c + i], p0, 0, 0, 0);
;                     p1 = __builtin_amdgcn_mfma_f32_32x32x16_bf16(kf[c & 1][2 * i + 1], qr[2 * c + i], p1, 0, 0, 0);
;                 }
;                 __builtin_amdgcn_sched_barrier(0);
;             }
;             if (more) ATT_GLOAD((FLAGS & AF_REV) ? t - 1 : t + 1);
;             bf16x8 vf[2][4];
; #pragma unroll
;             for (int ks = 0; ks < 4; ++ks) vf[0][ks] = *(const LAS bf16x8*)(vb + ks * 32);
;     ...
;             f32x2 rs2 = {0.f, 0.f};
; #pragma unroll
;             for (int r = 0; r < 16; ++r) { p0[r] = __builtin_amdgcn_exp2f(p0[r]); p1[r] = __builtin_amdgcn_exp2f(p1[r]); }
; #pragma unroll
;             for (int r = 0; r < 16; r += 2) { rs2 += (f32x2){p0[r], p0[r + 1]}; rs2 += (f32x2){p1[r], p1[r + 1]}; }
;             l += rs2.x + rs2.y;
;             bf16x8 pf[4];
;             pf[0] = pack_bf16x8(p0, 0); pf[1] = pack_bf16x8(p0, 8); pf[2] = pack_bf16x8(p1, 0); pf[3] = pack_bf16x8(p1, 8);
;             __builtin_amdgcn_sched_barrier(0);
; #pragma unroll
;             for (int d = 0; d < NDB; ++d) {
;                 if (d + 1 < NDB) {
; #pragma unroll
;                     for (int ks = 0; ks < 4; ++ks) vf[(d + 1) & 1][ks] = *(const LAS bf16x8*)(vb + (d + 1) * 32 * VROW + ks * 32);
;                 }
; #pragma unroll
;                 for (int ks = 0; ks < 4; ++ks) o[d] = __builtin_amdgcn_mfma_f32_32x32x16_bf16(vf[d & 1][ks], pf[ks], o[d], 0, 0, 0);
;                 __builtin_amdgcn_sched_barrier(0);
;             }
;         }
;         if (skip && more) ATT_GLOAD((FLAGS & AF_REV) ? t - 1 : t + 1);
;         if (more) ATT_LSTORE(cur ^ 1);
;         __syncthreads();
.Lq_top3:
	s_cmp_eq_u32 s3, 0
	s_cbranch_scc1 .Lq_gen3
	s_add_i32 s13, s3, 1
	s_cmp_ge_i32 s13, s20
	s_cbranch_scc1 .Lq_gen3
	ds_read_b128 v[96:99], v187 offset:0
	ds_read_b128 v[104:107], v187 offset:6656
	ds_read_b128 v[100:103], v187 offset:32
	ds_read_b128 v[108:111], v187 offset:6688
	ds_read_b128 v[112:115], v187 offset:64
	ds_read_b128 v[120:123], v187 offset:6720
	ds_read_b128 v[116:119], v187 offset:96
	ds_read_b128 v[124:127], v187 offset:6752
	v_mfma_f32_32x32x16_bf16 v[32:47], v[152:155], v[64:67], v[32:47]
	v_exp_f32_e32 v214, v214
	v_exp_f32_e32 v215, v215
	v_mfma_f32_32x32x16_bf16 v[16:31], v[188:191], v[64:67], v[16:31]
	v_exp_f32_e32 v230, v230
	v_exp_f32_e32 v231, v231
	v_add_f32_e32 v204, v214, v175
	s_waitcnt vmcnt(0)
	ds_write_b128 v14, v[140:143] offset:22528
	v_mfma_f32_32x32x16_bf16 v[32:47], v[156:159], v[68:71], v[32:47]
	v_exp_f32_e32 v216, v216
	v_exp_f32_e32 v217, v217
	v_add_f32_e32 v204, v230, v204
	v_add_f32_e32 v205, v215, v231
	ds_write_b128 v174, v[148:151] offset:35840
	v_mfma_f32_32x32x16_bf16 v[16:31], v[192:195], v[68:71], v[16:31]
	v_exp_f32_e32 v232, v232
	v_exp_f32_e32 v233, v233
	v_add_f32_e32 v204, v216, v204
	v_add_f32_e32 v205, v217, v205
	s_and_saveexec_b64 s[14:15], s[10:11]
	ds_write_b128 v172, v[144:147] offset:22528
	s_or_b64 exec, exec, s[14:15]
	v_mfma_f32_32x32x16_bf16 v[32:47], v[160:163], v[72:75], v[32:47]
	v_exp_f32_e32 v218, v218
	v_exp_f32_e32 v219, v219
	v_add_f32_e32 v204, v232, v204
	v_add_f32_e32 v205, v233, v205
	s_and_saveexec_b64 s[14:15], s[10:11]
	global_load_dwordx4 v[144:147], v180, s[98:99]
	s_or_b64 exec, exec, s[14:15]
	v_mfma_f32_32x32x16_bf16 v[16:31], v[196:199], v[72:75], v[16:31]
	v_exp_f32_e32 v234, v234
	v_exp_f32_e32 v235, v235
	v_add_f32_e32 v204, v218, v204
	v_add_f32_e32 v205, v219, v205
	global_load_dwordx4 v[140:143], v178, s[98:99]
	v_mfma_f32_32x32x16_bf16 v[32:47], v[164:167], v[76:79], v[32:47]
	v_exp_f32_e32 v220, v220
	v_exp_f32_e32 v221, v221
	v_add_f32_e32 v204, v234, v204
	v_add_f32_e32 v205, v235, v205
	global_load_dwordx4 v[148:151], v176, s[100:101]
	s_add_i32 s12, s3, 4
	s_cmp_lt_i32 s12, s2
	s_cselect_b32 s12, s96, 0
	s_cselect_b32 s13, 0x80, 0
	s_add_u32 s98, s98, s12
	s_addc_u32 s99, s99, 0
	s_add_u32 s100, s100, s13
	s_addc_u32 s101, s101, 0
	v_mfma_f32_32x32x16_bf16 v[16:31], v[200:203], v[76:79], v[16:31]
	v_exp_f32_e32 v236, v236
	v_exp_f32_e32 v237, v237
	v_add_f32_e32 v204, v220, v204
	v_add_f32_e32 v205, v221, v205
	ds_read_b128 v[152:155], v247 offset:35840
	ds_read_b128 v[156:159], v247 offset:35872
	ds_read_b128 v[160:163], v247 offset:35904
	ds_read_b128 v[164:167], v247 offset:35936
	s_waitcnt lgkmcnt(8)
	v_mfma_f32_32x32x16_bf16 v[64:79], v[96:99], v[2:5], v[48:63]
	v_exp_f32_e32 v222, v222
	v_exp_f32_e32 v223, v223
	v_add_f32_e32 v204, v236, v204
	v_add_f32_e32 v205, v237, v205
	v_mfma_f32_32x32x16_bf16 v[80:95], v[104:107], v[2:5], v[48:63]
	v_exp_f32_e32 v238, v238
	v_exp_f32_e32 v239, v239
	v_add_f32_e32 v204, v222, v204
	v_add_f32_e32 v205, v223, v205
	v_mfma_f32_32x32x16_bf16 v[64:79], v[100:103], v[6:9], v[64:79]
	v_exp_f32_e32 v224, v224
	v_exp_f32_e32 v225, v225
	v_add_f32_e32 v204, v238, v204
	v_add_f32_e32 v205, v239, v205
	v_mfma_f32_32x32x16_bf16 v[80:95], v[108:111], v[6:9], v[80:95]
	v_exp_f32_e32 v240, v240
	v_exp_f32_e32 v241, v241
	v_add_f32_e32 v204, v224, v204
	v_add_f32_e32 v205, v225, v205
	ds_read_b128 v[96:99], v187 offset:128
	ds_read_b128 v[104:107], v187 offset:6784
	ds_read_b128 v[100:103], v187 offset:160
	ds_read_b128 v[108:111], v187 offset:6816
	s_waitcnt lgkmcnt(8)
	v_mfma_f32_32x32x16_bf16 v[64:79], v[112:115], v[10:13], v[64:79]
	v_exp_f32_e32 v226, v226
	v_exp_f32_e32 v227, v227
	v_add_f32_e32 v204, v240, v204
	v_add_f32_e32 v205, v241, v205
	v_mfma_f32_32x32x16_bf16 v[80:95], v[120:123], v[10:13], v[80:95]
	v_exp_f32_e32 v242, v242
	v_exp_f32_e32 v243, v243
	v_add_f32_e32 v204, v226, v204
	v_add_f32_e32 v205, v227, v205
	v_mfma_f32_32x32x16_bf16 v[64:79], v[116:119], v[128:131], v[64:79]
	v_exp_f32_e32 v228, v228
	v_exp_f32_e32 v229, v229
	v_add_f32_e32 v204, v242, v204
	v_add_f32_e32 v205, v243, v205
	v_mfma_f32_32x32x16_bf16 v[80:95], v[124:127], v[128:131], v[80:95]
	v_exp_f32_e32 v244, v244
	v_exp_f32_e32 v245, v245
	v_add_f32_e32 v204, v228, v204
	v_add_f32_e32 v205, v229, v205
	ds_read_b128 v[188:191], v247 offset:40448
	ds_read_b128 v[192:195], v247 offset:40480
	ds_read_b128 v[196:199], v247 offset:40512
	ds_read_b128 v[200:203], v247 offset:40544
	s_waitcnt lgkmcnt(4)
	v_mfma_f32_32x32x16_bf16 v[64:79], v[96:99], v[132:135], v[64:79]
	s_nop 0
	v_add_f32_e32 v204, v244, v204
	v_add_f32_e32 v205, v245, v205
	v_cvt_pk_bf16_f32 v214, v214, v215
	v_cvt_pk_bf16_f32 v215, v216, v217
	v_cvt_pk_bf16_f32 v216, v218, v219
	v_mfma_f32_32x32x16_bf16 v[80:95], v[104:107], v[132:135], v[80:95]
	v_cvt_pk_bf16_f32 v217, v220, v221
	v_cvt_pk_bf16_f32 v218, v222, v223
	v_cvt_pk_bf16_f32 v219, v224, v225
	v_cvt_pk_bf16_f32 v220, v226, v227
	v_cvt_pk_bf16_f32 v221, v228, v229
	v_mfma_f32_32x32x16_bf16 v[64:79], v[100:103], v[136:139], v[64:79]
	v_cvt_pk_bf16_f32 v222, v230, v231
	v_cvt_pk_bf16_f32 v223, v232, v233
	v_cvt_pk_bf16_f32 v224, v234, v235
	v_cvt_pk_bf16_f32 v225, v236, v237
	v_cvt_pk_bf16_f32 v226, v238, v239
	v_mfma_f32_32x32x16_bf16 v[80:95], v[108:111], v[136:139], v[80:95]
	v_cvt_pk_bf16_f32 v227, v240, v241
	v_cvt_pk_bf16_f32 v228, v242, v243
	v_cvt_pk_bf16_f32 v229, v244, v245
	v_add_f32_e32 v175, v204, v205
.Lq_tailb3:
	s_add_i32 s3, s3, 1
	s_cmp_ge_i32 s3, s2
	s_cbranch_scc1 .Lq_flush0
	s_waitcnt lgkmcnt(0)
	s_barrier
	s_branch .Lq_top0
.Lq_gen0:
	s_add_i32 s13, s3, 1
	s_cmp_ge_i32 s13, s20
	s_cbranch_scc1 .Lq_nokr_q0
	s_add_i32 s12, s3, 1
	s_and_b32 s12, s12, 3
	s_mulk_i32 s12, 0x5800
	v_add3_u32 v206, s12, v169, v0
	ds_read_b128 v[96:99], v206 offset:0
	ds_read_b128 v[104:107], v206 offset:6656
	ds_read_b128 v[100:103], v206 offset:32
	ds_read_b128 v[108:111], v206 offset:6688
	ds_read_b128 v[112:115], v206 offset:64
	ds_read_b128 v[120:123], v206 offset:6720
	ds_read_b128 v[116:119], v206 offset:96
	ds_read_b128 v[124:127], v206 offset:6752

; #define ATT_LSTORE(buf) do { LAS unsigned char* b_ = lds + (buf) * BUF; \
;         _Pragma("unroll") for (int i = 0; i < KPT; ++i) { if (KCH % NTHREADS == 0 || tid + i * NTHREADS < KCH) *(LAS u32x4*)(b_ + klo[i]) = kreg[i]; } \
;         _Pragma("unroll") for (int i = 0; i < VPT; ++i) *(LAS u32x4*)(b_ + vlo[i]) = vreg[i]; } while (0)
; template <int DQK, int DV, int FLAGS, int qp, int kp, int vts, int op> ...
;     ...
;         if (more) ATT_LSTORE(cur ^ 1);
;         __syncthreads();
.Lq_noqk_q0:
.Lq_tail0:
	s_add_i32 s12, s3, 2
	s_cmp_ge_i32 s12, s2
	s_cbranch_scc1 .Lq_nols_q0
	s_and_b32 s16, s12, 3
	s_mulk_i32 s16, 0x5800
	s_waitcnt vmcnt(0)
	v_add_u32_e32 v209, s16, v14
	v_add_u32_e32 v210, s16, v174
	v_add_u32_e32 v211, s16, v172
	ds_write_b128 v209, v[140:143]
	ds_write_b128 v210, v[148:151] offset:13312
	s_and_saveexec_b64 s[14:15], s[10:11]
	ds_write_b128 v211, v[144:147]
	s_or_b64 exec, exec, s[14:15]
	s_add_i32 s12, s3, 3
	s_cmp_ge_i32 s12, s2
	s_cbranch_scc1 .Lq_nols_q0
	s_and_saveexec_b64 s[14:15], s[10:11]
	global_load_dwordx4 v[144:147], v180, s[98:99]
	s_or_b64 exec, exec, s[14:15]
	global_load_dwordx4 v[140:143], v178, s[98:99]
	global_load_dwordx4 v[148:151], v176, s[100:101]
	s_add_u32 s98, s98, s96
	s_addc_u32 s99, s99, s97
	s_add_u32 s100, s100, 0x80
	s_addc_u32 s101, s101, 0
.Lq_nols_q0:
	s_branch .Lq_tailb0
.Lq_gen1:
	s_add_i32 s13, s3, 1
	s_cmp_ge_i32 s13, s20
	s_cbranch_scc1 .Lq_nokr_q1
	s_add_i32 s12, s3, 1
	s_and_b32 s12, s12, 3
	s_mulk_i32 s12, 0x5800
	v_add3_u32 v206, s12, v169, v0
	ds_read_b128 v[96:99], v206 offset:0
	ds_read_b128 v[104:107], v206 offset:6656
	ds_read_b128 v[100:103], v206 offset:32
	ds_read_b128 v[108:111], v206 offset:6688
	ds_read_b128 v[112:115], v206 offset:64
	ds_read_b128 v[120:123], v206 offset:6720
	ds_read_b128 v[116:119], v206 offset:96
	ds_read_b128 v[124:127], v206 offset:6752

; #define ATT_LSTORE(buf) do { LAS unsigned char* b_ = lds + (buf) * BUF; \
;         _Pragma("unroll") for (int i = 0; i < KPT; ++i) { if (KCH % NTHREADS == 0 || tid + i * NTHREADS < KCH) *(LAS u32x4*)(b_ + klo[i]) = kreg[i]; } \
;         _Pragma("unroll") for (int i = 0; i < VPT; ++i) *(LAS u32x4*)(b_ + vlo[i]) = vreg[i]; } while (0)
; template <int DQK, int DV, int FLAGS, int qp, int kp, int vts, int op> ...
;     ...
;         if (more) ATT_LSTORE(cur ^ 1);
;         __syncthreads();
.Lq_noqk_q1:
.Lq_tail1:
	s_add_i32 s12, s3, 2
	s_cmp_ge_i32 s12, s2
	s_cbranch_scc1 .Lq_nols_q1
	s_and_b32 s16, s12, 3
	s_mulk_i32 s16, 0x5800
	s_waitcnt vmcnt(0)
	v_add_u32_e32 v209, s16, v14
	v_add_u32_e32 v210, s16, v174
	v_add_u32_e32 v211, s16, v172
	ds_write_b128 v209, v[140:143]
	ds_write_b128 v210, v[148:151] offset:13312
	s_and_saveexec_b64 s[14:15], s[10:11]
	ds_write_b128 v211, v[144:147]
	s_or_b64 exec, exec, s[14:15]
	s_add_i32 s12, s3, 3
	s_cmp_ge_i32 s12, s2
	s_cbranch_scc1 .Lq_nols_q1
	s_and_saveexec_b64 s[14:15], s[10:11]
	global_load_dwordx4 v[144:147], v180, s[98:99]
	s_or_b64 exec, exec, s[14:15]
	global_load_dwordx4 v[140:143], v178, s[98:99]
	global_load_dwordx4 v[148:151], v176, s[100:101]
	s_add_u32 s98, s98, s96
	s_addc_u32 s99, s99, s97
	s_add_u32 s100, s100, 0x80
	s_addc_u32 s101, s101, 0
.Lq_nols_q1:
	s_branch .Lq_tailb1
.Lq_gen2:
	s_add_i32 s13, s3, 1
	s_cmp_ge_i32 s13, s20
	s_cbranch_scc1 .Lq_nokr_q2
	s_add_i32 s12, s3, 1
	s_and_b32 s12, s12, 3
	s_mulk_i32 s12, 0x5800
	v_add3_u32 v206, s12, v169, v0
	ds_read_b128 v[96:99], v206 offset:0
	ds_read_b128 v[104:107], v206 offset:6656
	ds_read_b128 v[100:103], v206 offset:32
	ds_read_b128 v[108:111], v206 offset:6688
	ds_read_b128 v[112:115], v206 offset:64
	ds_read_b128 v[120:123], v206 offset:6720
	ds_read_b128 v[116:119], v206 offset:96
	ds_read_b128 v[124:127], v206 offset:6752

; #define ATT_LSTORE(buf) do { LAS unsigned char* b_ = lds + (buf) * BUF; \
;         _Pragma("unroll") for (int i = 0; i < KPT; ++i) { if (KCH % NTHREADS == 0 || tid + i * NTHREADS < KCH) *(LAS u32x4*)(b_ + klo[i]) = kreg[i]; } \
;         _Pragma("unroll") for (int i = 0; i < VPT; ++i) *(LAS u32x4*)(b_ + vlo[i]) = vreg[i]; } while (0)
; template <int DQK, int DV, int FLAGS, int qp, int kp, int vts, int op> ...
;     ...
;         if (more) ATT_LSTORE(cur ^ 1);
;         __syncthreads();
.Lq_noqk_q2:
.Lq_tail2:
	s_add_i32 s12, s3, 2
	s_cmp_ge_i32 s12, s2
	s_cbranch_scc1 .Lq_nols_q2
	s_and_b32 s16, s12, 3
	s_mulk_i32 s16, 0x5800
	s_waitcnt vmcnt(0)
	v_add_u32_e32 v209, s16, v14
	v_add_u32_e32 v210, s16, v174
	v_add_u32_e32 v211, s16, v172
	ds_write_b128 v209, v[140:143]
	ds_write_b128 v210, v[148:151] offset:13312
	s_and_saveexec_b64 s[14:15], s[10:11]
	ds_write_b128 v211, v[144:147]
	s_or_b64 exec, exec, s[14:15]
	s_add_i32 s12, s3, 3
	s_cmp_ge_i32 s12, s2
	s_cbranch_scc1 .Lq_nols_q2
	s_and_saveexec_b64 s[14:15], s[10:11]
	global_load_dwordx4 v[144:147], v180, s[98:99]
	s_or_b64 exec, exec, s[14:15]
	global_load_dwordx4 v[140:143], v178, s[98:99]
	global_load_dwordx4 v[148:151], v176, s[100:101]
	s_add_u32 s98, s98, s96
	s_addc_u32 s99, s99, s97
	s_add_u32 s100, s100, 0x80
	s_addc_u32 s101, s101, 0
.Lq_nols_q2:
	s_branch .Lq_tailb2
.Lq_gen3:
	s_add_i32 s13, s3, 1
	s_cmp_ge_i32 s13, s20
	s_cbranch_scc1 .Lq_nokr_q3
	s_add_i32 s12, s3, 1
	s_and_b32 s12, s12, 3
	s_mulk_i32 s12, 0x5800
	v_add3_u32 v206, s12, v169, v0
	ds_read_b128 v[96:99], v206 offset:0
	ds_read_b128 v[104:107], v206 offset:6656
	ds_read_b128 v[100:103], v206 offset:32
	ds_read_b128 v[108:111], v206 offset:6688
	ds_read_b128 v[112:115], v206 offset:64
	ds_read_b128 v[120:123], v206 offset:6720
	ds_read_b128 v[116:119], v206 offset:96
	ds_read_b128 v[124:127], v206 offset:6752

; #define ATT_LSTORE(buf) do { LAS unsigned char* b_ = lds + (buf) * BUF; \
;         _Pragma("unroll") for (int i = 0; i < KPT; ++i) { if (KCH % NTHREADS == 0 || tid + i * NTHREADS < KCH) *(LAS u32x4*)(b_ + klo[i]) = kreg[i]; } \
;         _Pragma("unroll") for (int i = 0; i < VPT; ++i) *(LAS u32x4*)(b_ + vlo[i]) = vreg[i]; } while (0)
; template <int DQK, int DV, int FLAGS, int qp, int kp, int vts, int op> ...
;     ...
;                 for (int ks = 0; ks < 4; ++ks) o[d] = __builtin_amdgcn_mfma_f32_32x32x16_bf16(vf[d & 1][ks], pf[ks], o[d], 0, 0, 0);
;                 __builtin_amdgcn_sched_barrier(0);
;             }
;         }
;         if (skip && more) ATT_GLOAD((FLAGS & AF_REV) ? t - 1 : t + 1);
;         if (more) ATT_LSTORE(cur ^ 1);
;         __syncthreads();
.Lq_noqk_q3:
.Lq_tail3:
	s_add_i32 s12, s3, 2
	s_cmp_ge_i32 s12, s2
	s_cbranch_scc1 .Lq_nols_q3
	s_and_b32 s16, s12, 3
	s_mulk_i32 s16, 0x5800
	s_waitcnt vmcnt(0)
	v_add_u32_e32 v209, s16, v14
	v_add_u32_e32 v210, s16, v174
	v_add_u32_e32 v211, s16, v172
	ds_write_b128 v209, v[140:143]
	ds_write_b128 v210, v[148:151] offset:13312
	s_and_saveexec_b64 s[14:15], s[10:11]
	ds_write_b128 v211, v[144:147]
	s_or_b64 exec, exec, s[14:15]
	s_add_i32 s12, s3, 3
	s_cmp_ge_i32 s12, s2
	s_cbranch_scc1 .Lq_nols_q3
	s_and_saveexec_b64 s[14:15], s[10:11]
	global_load_dwordx4 v[144:147], v180, s[98:99]
	s_or_b64 exec, exec, s[14:15]
	global_load_dwordx4 v[140:143], v178, s[98:99]
	global_load_dwordx4 v[148:151], v176, s[100:101]
	s_add_u32 s98, s98, s96
	s_addc_u32 s99, s99, s97
	s_add_u32 s100, s100, 0x80
	s_addc_u32 s101, s101, 0
.Lq_nols_q3:
	s_branch .Lq_tailb3
.Lq_flush0:
	s_cmp_lt_i32 s20, s2
	s_cbranch_scc1 .LBB0_572
	s_waitcnt lgkmcnt(0)
	v_mfma_f32_32x32x16_bf16 v[32:47], v[152:155], v[214:217], v[32:47]
	v_mfma_f32_32x32x16_bf16 v[16:31], v[188:191], v[214:217], v[16:31]
	v_mfma_f32_32x32x16_bf16 v[32:47], v[156:159], v[218:221], v[32:47]
	v_mfma_f32_32x32x16_bf16 v[16:31], v[192:195], v[218:221], v[16:31]
	v_mfma_f32_32x32x16_bf16 v[32:47], v[160:163], v[222:225], v[32:47]
	v_mfma_f32_32x32x16_bf16 v[16:31], v[196:199], v[222:225], v[16:31]
	v_mfma_f32_32x32x16_bf16 v[32:47], v[164:167], v[226:229], v[32:47]
	v_mfma_f32_32x32x16_bf16 v[16:31], v[200:203], v[226:229], v[16:31]
	s_branch .LBB0_572
